# split scan/attention without attention throttle, downstream code pinned to the reference placement
# speedup vs baseline: 1.0130x; 1.0130x over previous
; __global__ void __launch_bounds__(512, 2) fwd_kernel(Params p) {
;     ...
;             phase_scan2(p, l, lds);
;             phase_attn(p, l, lds);
;             xcd_barrier(xb);
;             phase_post(p, l);
.Lat_end:
	v_readlane_b32 s52, v243, 41
	v_readlane_b32 s53, v243, 42
	v_readlane_b32 s80, v252, 4
	v_readlane_b32 s81, v252, 5
	v_readlane_b32 s82, v252, 6
	v_readlane_b32 s83, v252, 7
	v_readlane_b32 s84, v252, 8
	v_readlane_b32 s85, v252, 9
	v_readlane_b32 s86, v252, 10
	v_readlane_b32 s87, v252, 11
	v_readlane_b32 s88, v252, 12
	v_readlane_b32 s89, v252, 13
	v_readlane_b32 s90, v252, 14
	v_readlane_b32 s91, v252, 15
	v_readlane_b32 s92, v252, 16
	v_readlane_b32 s93, v252, 17
	v_readlane_b32 s94, v252, 18
	v_readlane_b32 s95, v252, 19
	s_waitcnt vmcnt(0)
	.p2align 8
	s_nop 0
	s_nop 0
	s_nop 0
	s_nop 0
	s_nop 0
	s_nop 0
	s_nop 0
	s_nop 0
	s_nop 0
	s_nop 0
	s_nop 0
	s_nop 0
	s_nop 0
	s_nop 0
	s_nop 0
	s_nop 0
	s_nop 0
	s_nop 0
	s_nop 0
